# attention prologue: redundant second sink load removed (row group 1 reuses row group 0's value)
# baseline (speedup 1.0000x reference)
.LBB0_109:
	s_and_b64 vcc, exec, s[40:41]
	s_cbranch_vccnz .LBB0_111
	v_mov_b32_e32 v225, v187
	v_mov_b32_e32 v226, v227
